# speedup vs baseline: 1.0055x; 1.0028x over previous
; #define otid() otid_(wid_s_)
; #define SLOAD(k0) do { SLOAD_KR(k0); SLOAD_V(k0); } while (0)
; #define SWRITE(b) do { SWRITE_KR(b); SWRITE_V(b); } while (0)
; #define SWAIT() asm volatile("s_waitcnt vmcnt(0)" ::: "memory")
; DEVI void attn_item(const u16* __restrict__ Qb, const u16* __restrict__ KNh, const u16* __restrict__ VTh, int Lpad, const u16* __restrict__ KRb,
;                     const u16* __restrict__ SZb, u16* __restrict__ AOb, int NT, char* lds, const int wid_s_) {
;   const int tid = otid(), wid = tid >> 6, lane = tid & 63, r32 = lane & 31, hi = lane >> 5;
;   char* V_lds = lds; char* K_lds = lds + 2 * SHM_V; char* R_lds = lds + 2 * SHM_V + 2 * SHM_K;
;   char* Qrs = lds + 2 * SHM_V + 2 * SHM_K + 2 * SHM_R + wid * 4096;
;   float* wsf = (float*)(lds + 2 * SHM_V + 2 * SHM_K + 2 * SHM_R + 32768) + wid * 64; float* li_l = wsf; float* al_l = wsf + 32;
;   float m_reg = -1e30f, l_reg = 0; f32x16 o[4] = {}; bf16x8 qr[8];
;   const u16* Qw = Qb + (size_t)(wid * 32 + r32) * LDQ + hi * 8;
; #pragma unroll
;   for (int d0 = 0; d0 < 8; ++d0) qr[d0] = __builtin_nontemporal_load(reinterpret_cast<const bf16x8*>(Qw + d0 * 16));
; #pragma unroll
;   for (int d0 = 0; d0 < 4; ++d0) *reinterpret_cast<bf16x8*>(Qrs + RSWZ(r32, (d0 * 16 + hi * 8) * 2)) = *reinterpret_cast<const bf16x8*>(Qw + 128 + d0 * 16);
;   const int sr = tid >> 4, sc = (tid & 15) * 8;
;   const int vd = tid >> 3, vc = tid & 7;
;   const int rr_ = tid >> 3, rc_ = (tid & 7) * 8;
;   bf16x8 vs0, vs1, ks0, ks1, rs0;
;   const unsigned vo_k = (unsigned)((sr * LDK + sc) * 2), vo_r = (unsigned)((rr_ * 64 + rc_) * 2), vo_v = (unsigned)((vd * Lpad + vc * 8) * 2);
;   const size_t vhalf = (size_t)64 * Lpad * 2;
;     ...
;   f32x16 pA0, pA1, pB0, pB1; float mnA, mnB, alA, alB; bf16x8 pa0, pa1, pa2, pa3;
;   SLOAD(0); SWAIT(); SWRITE(0); __syncthreads();
; DEVI void phase_e(const Params& p, const Pass& ps, char* shm, const int wid_s_) {
;     ...
;     int item = (it * 8 + xcd) * per + slot; if (item >= items) break;
;     int qb = item % nqb, bh = item / nqb, h = bh & 15, b = bh >> 4;
;     size_t row0 = (size_t)b * ps.S + (size_t)qb * 256;
;     attn_item(Q + row0 * LDQ + h * 192, KN + (size_t)b * ps.Lpad * LDK + h * 128, VT + (size_t)((b * 16 + h) * 128) * ps.Lpad, ps.Lpad, KR + (size_t)b * ps.Lpad * 64,
.LBB0_980:
	s_lshr_b32 s2, s1, s93
	s_and_b32 s46, s1, s31
	s_lshr_b32 s8, s2, 4
	s_and_b32 s1, s2, 15
	s_mul_i32 s13, s8, s29
	s_lshl_b64 s[6:7], s[46:47], 8
	s_mul_hi_u32 s9, s8, s29
	s_add_u32 s56, s13, s6
	s_addc_u32 s57, s9, s7
	s_mul_i32 s6, s57, 0x1800
	s_mul_hi_u32 s7, s56, 0x1800
	s_add_i32 s7, s7, s6
	s_mul_i32 s6, s56, 0x1800
	s_add_u32 s6, s94, s6
	s_addc_u32 s7, s95, s7
	s_mul_i32 s9, s1, 0x180
	s_add_u32 s14, s6, s9
	s_mul_hi_u32 s17, s8, s28
	s_mul_i32 s16, s8, s28
	s_addc_u32 s15, s7, 0
	s_lshl_b64 s[8:9], s[16:17], 12
	s_add_u32 s6, s52, s8
	v_mov_b32_e32 v51, v207
	s_addc_u32 s7, s53, s9
	s_lshl_b32 s35, s1, 7
	s_lshl_b32 s1, s1, 8
	s_add_u32 s18, s6, s1
	v_ashrrev_i32_e32 v40, 6, v51
	v_and_b32_e32 v176, 31, v51
	v_lshlrev_b32_e32 v175, 5, v40
	s_addc_u32 s19, s7, 0
	s_lshl_b32 s46, s2, 7
	v_bfe_u32 v174, v51, 5, 1
	v_or_b32_e32 v2, v175, v176
	v_mov_b64_e32 v[0:1], s[14:15]
	v_lshlrev_b32_e32 v42, 4, v51
	s_mul_hi_u32 s7, s46, s28
	s_mul_i32 s6, s46, s28
	v_mad_i64_i32 v[0:1], s[14:15], v2, s89, v[0:1]
	v_lshlrev_b32_e32 v160, 4, v174
	v_mov_b32_e32 v161, v205
	v_ashrrev_i32_e32 v41, 4, v51
	v_and_b32_e32 v49, 0xf0, v42
	v_ashrrev_i32_e32 v16, 3, v51
	s_lshl_b64 s[6:7], s[6:7], 1
	v_lshl_add_u64 v[38:39], v[0:1], 0, v[160:161]
	v_lshl_or_b32 v204, v41, 12, v49
	v_lshlrev_b32_e32 v43, 7, v16
	v_and_b32_e32 v17, 0x70, v42
	v_mul_lo_u32 v16, s5, v16
	s_add_u32 s6, s70, s6
	global_load_dwordx4 v[0:3], v[38:39], off offset:256
	global_load_dwordx4 v[4:7], v[38:39], off offset:288
	global_load_dwordx4 v[8:11], v[38:39], off offset:320
	global_load_dwordx4 v[12:15], v[38:39], off offset:352
	v_or_b32_e32 v48, v43, v17
	v_or_b32_e32 v50, v17, v16
	v_lshl_add_u64 v[16:17], s[18:19], 0, v[204:205]
	s_mov_b32 s2, 0x20000
	s_addc_u32 s7, s71, s7
	s_lshl_b64 s[58:59], s[16:17], 7
	v_add_co_u32_e32 v22, vcc, s2, v16
	s_add_u32 s16, s44, s58
	s_nop 0
	v_addc_co_u32_e32 v23, vcc, 0, v17, vcc
	s_addc_u32 s17, s45, s59
	global_load_dwordx4 v[18:21], v204, s[18:19]
	s_nop 0
	global_load_dwordx4 v[22:25], v[22:23], off
	s_nop 0
	global_load_dwordx4 v[26:29], v48, s[16:17]
	s_add_u32 s14, s6, s54
	s_addc_u32 s15, s7, 0
	global_load_dwordx4 v[30:33], v50, s[6:7]
	global_load_dwordx4 v[34:37], v50, s[14:15]
	global_load_dwordx4 v[96:99], v[38:39], off nt
	global_load_dwordx4 v[100:103], v[38:39], off offset:32 nt
	global_load_dwordx4 v[104:107], v[38:39], off offset:64 nt
	global_load_dwordx4 v[108:111], v[38:39], off offset:96 nt
	global_load_dwordx4 v[112:115], v[38:39], off offset:128 nt
	global_load_dwordx4 v[116:119], v[38:39], off offset:160 nt
	global_load_dwordx4 v[120:123], v[38:39], off offset:192 nt
	global_load_dwordx4 v[124:127], v[38:39], off offset:224 nt
	v_mov_b32_e32 v45, 0x14000
	v_lshlrev_b32_e32 v44, 3, v51
	v_lshl_add_u32 v183, v40, 12, v45
	v_lshlrev_b32_e32 v72, 7, v176
	v_and_b32_e32 v73, 0x70, v44
	v_or_b32_e32 v40, v183, v72
	v_bitop3_b32 v44, v160, v44, s90 bitop3:0x78
	v_bitop3_b32 v45, v160, v73, 32 bitop3:0x36
	v_bitop3_b32 v46, v160, v73, 64 bitop3:0x36
	v_or_b32_e32 v44, v40, v44
	v_or_b32_e32 v45, v40, v45
	s_movk_i32 s2, 0x60
	v_or_b32_e32 v74, 64, v160
	v_or_b32_e32 v75, 0x60, v160
	v_bitop3_b32 v177, v160, v72, v73 bitop3:0xde
	v_or_b32_e32 v195, 0x10000, v177
	v_or_b32_e32 v196, 0x11000, v177
	v_bitop3_b32 v180, v74, v72, v73 bitop3:0xde
	v_or_b32_e32 v199, 0x10000, v180
	v_or_b32_e32 v200, 0x11000, v180
	s_waitcnt vmcnt(16)
	ds_write_b128 v44, v[0:3]
	s_waitcnt vmcnt(15)
	ds_write_b128 v45, v[4:7]
	v_or_b32_e32 v0, v40, v46
	s_waitcnt vmcnt(14)
	ds_write_b128 v0, v[8:11]
	v_bitop3_b32 v0, v160, v73, s2 bitop3:0x36
	v_or_b32_e32 v0, v40, v0
	v_xor_b32_e32 v1, v42, v51
	s_waitcnt vmcnt(13)
	ds_write_b128 v0, v[12:15]
	v_lshlrev_b32_e32 v0, 8, v41
	s_movk_i32 s2, 0xf0
	v_and_or_b32 v185, v1, s90, v43
	v_and_or_b32 v184, v1, s2, v0
	v_add_u32_e32 v186, 0x10000, v185
	s_waitcnt vmcnt(0)
	s_waitcnt vmcnt(12)
	ds_write_b128 v184, v[18:21] offset:32768
	s_waitcnt vmcnt(11)
	ds_write_b128 v184, v[22:25] offset:40960
	s_waitcnt vmcnt(10)
	ds_write_b128 v186, v[26:29]
	s_waitcnt vmcnt(9)
	ds_write_b128 v185, v[30:33]
	s_waitcnt vmcnt(8)
	ds_write_b128 v185, v[34:37] offset:8192
	v_lshlrev_b32_e32 v26, 8, v176
	v_bitop3_b32 v187, v160, v26, v49 bitop3:0xde
	s_waitcnt lgkmcnt(0)
	s_barrier
; #define SLOAD(k0) do { SLOAD_KR(k0); SLOAD_V(k0); } while (0)
; #define SWRITE(b) do { SWRITE_KR(b); SWRITE_V(b); } while (0)
; #define SWAIT() asm volatile("s_waitcnt vmcnt(0)" ::: "memory")
; DEVI void qkt(f32x16& p0, f32x16& p1, const char* Ks, const char* Rs, const bf16x8* qr, const char* Qrs, int r32, int hi) {
;   p0 = f32x16{}; p1 = f32x16{};
; #pragma unroll
;   for (int d0 = 0; d0 < 8; ++d0) { int cb = (d0 * 16 + hi * 8) * 2;
;     bf16x8 b0 = *reinterpret_cast<const bf16x8*>(Ks + KSWZ(r32, cb));
;     bf16x8 b1 = *reinterpret_cast<const bf16x8*>(Ks + KSWZ(32 + r32, cb));
;     p0 = __builtin_amdgcn_mfma_f32_32x32x16_bf16(b0, qr[d0], p0, 0, 0, 0);
;     p1 = __builtin_amdgcn_mfma_f32_32x32x16_bf16(b1, qr[d0], p1, 0, 0, 0); }
; #pragma unroll
;   for (int d0 = 0; d0 < 4; ++d0) { int cb = (d0 * 16 + hi * 8) * 2;
;     bf16x8 b0 = *reinterpret_cast<const bf16x8*>(Rs + RSWZ(r32, cb));
;     bf16x8 b1 = *reinterpret_cast<const bf16x8*>(Rs + RSWZ(32 + r32, cb));
;     bf16x8 qf = *reinterpret_cast<const bf16x8*>(Qrs + RSWZ(r32, cb));
;     p0 = __builtin_amdgcn_mfma_f32_32x32x16_bf16(b0, qf, p0, 0, 0, 0);
;     p1 = __builtin_amdgcn_mfma_f32_32x32x16_bf16(b1, qf, p1, 0, 0, 0); }
; }
; DEVI void attn_item(const u16* __restrict__ Qb, const u16* __restrict__ KNh, const u16* __restrict__ VTh, int Lpad, const u16* __restrict__ KRb,
;                     const u16* __restrict__ SZb, u16* __restrict__ AOb, int NT, char* lds, const int wid_s_) {
;     ...
;   SLOAD(0); SWAIT(); SWRITE(0); __syncthreads();
;   qkt(pA0, pA1, K_lds, R_lds, qr, Qrs, r32, hi); partialSM(pA0, pA1, m_reg, mnA, alA);
;   SLOAD(64);
;   SWAIT(); SWRITE(1); __syncthreads();
	ds_read_b128 v[0:3], v187 offset:32768
	ds_read_b128 v[18:21], v187 offset:40960
	s_waitcnt vmcnt(7) lgkmcnt(1)
	v_mfma_f32_32x32x16_bf16 v[0:15], v[0:3], v[96:99], 0
	v_or_b32_e32 v27, 32, v160
	v_bitop3_b32 v188, v27, v26, v49 bitop3:0xde
	v_bitop3_b32 v189, v74, v26, v49 bitop3:0xde
	v_bitop3_b32 v190, v75, v26, v49 bitop3:0xde
	v_bitop3_b32 v161, v27, v72, v73 bitop3:0xde
	v_or_b32_e32 v197, 0x10000, v161
	s_mov_b32 s2, 0x40000
	s_waitcnt lgkmcnt(0)
	v_mfma_f32_32x32x16_bf16 v[32:47], v[18:21], v[96:99], 0
	ds_read_b128 v[18:21], v188 offset:32768
	ds_read_b128 v[22:25], v188 offset:40960
	v_or_b32_e32 v198, 0x11000, v161
	v_bitop3_b32 v179, v75, v72, v73 bitop3:0xde
	v_or_b32_e32 v201, 0x10000, v179
	v_or_b32_e32 v202, 0x11000, v179
	v_add_u32_e32 v203, 0x12000, v185
	s_mov_b32 s26, s12
	s_waitcnt vmcnt(6) lgkmcnt(1)
	v_mfma_f32_32x32x16_bf16 v[0:15], v[18:21], v[100:103], v[0:15]
	s_mov_b32 s27, s12
	s_mov_b32 s13, s12
	s_mov_b32 s18, s12
	s_mov_b32 s19, s12
	s_mov_b32 s20, s12
	s_mov_b32 s21, s12
	s_mov_b32 s22, s12
	s_waitcnt lgkmcnt(0)
	v_mfma_f32_32x32x16_bf16 v[32:47], v[22:25], v[100:103], v[32:47]
	ds_read_b128 v[18:21], v189 offset:32768
	ds_read_b128 v[22:25], v189 offset:40960
	s_mov_b32 s23, s12
	s_mov_b32 s24, s12
	s_mov_b32 s25, s12
	v_mov_b32_e32 v182, 0
	s_waitcnt vmcnt(5) lgkmcnt(1)
	v_mfma_f32_32x32x16_bf16 v[0:15], v[18:21], v[104:107], v[0:15]
	s_waitcnt lgkmcnt(0)
	v_mfma_f32_32x32x16_bf16 v[32:47], v[22:25], v[104:107], v[32:47]
	ds_read_b128 v[18:21], v190 offset:32768
	ds_read_b128 v[22:25], v190 offset:40960
	s_waitcnt vmcnt(4) lgkmcnt(1)
	v_mfma_f32_32x32x16_bf16 v[0:15], v[18:21], v[108:111], v[0:15]
	v_or_b32_e32 v18, 0x80, v160
	v_bitop3_b32 v191, v18, v26, v49 bitop3:0xde
	s_waitcnt lgkmcnt(0)
	v_mfma_f32_32x32x16_bf16 v[32:47], v[22:25], v[108:111], v[32:47]
	ds_read_b128 v[18:21], v191 offset:32768
	ds_read_b128 v[22:25], v191 offset:40960
	s_waitcnt vmcnt(3) lgkmcnt(1)
	v_mfma_f32_32x32x16_bf16 v[0:15], v[18:21], v[112:115], v[0:15]
	v_or_b32_e32 v18, 0xa0, v160
	v_bitop3_b32 v192, v18, v26, v49 bitop3:0xde
	s_waitcnt lgkmcnt(0)
	v_mfma_f32_32x32x16_bf16 v[32:47], v[22:25], v[112:115], v[32:47]
	ds_read_b128 v[18:21], v192 offset:32768
	ds_read_b128 v[22:25], v192 offset:40960
	s_waitcnt vmcnt(2) lgkmcnt(1)
	v_mfma_f32_32x32x16_bf16 v[0:15], v[18:21], v[116:119], v[0:15]
	v_or_b32_e32 v18, 0xc0, v160
	v_bitop3_b32 v193, v18, v26, v49 bitop3:0xde
	s_waitcnt lgkmcnt(0)
	v_mfma_f32_32x32x16_bf16 v[32:47], v[22:25], v[116:119], v[32:47]
	ds_read_b128 v[18:21], v193 offset:32768
	ds_read_b128 v[22:25], v193 offset:40960
	s_waitcnt vmcnt(1) lgkmcnt(1)
	v_mfma_f32_32x32x16_bf16 v[0:15], v[18:21], v[120:123], v[0:15]
	v_or_b32_e32 v18, 0xe0, v160
	v_bitop3_b32 v194, v18, v26, v49 bitop3:0xde
	v_mov_b32_e32 v49, v205
	v_lshl_add_u64 v[30:31], s[16:17], 0, v[48:49]
	s_mov_b32 s16, s12
	s_mov_b32 s17, s12
	v_lshl_add_u64 v[166:167], s[58:59], 0, v[48:49]
	v_add_u32_e32 v166, 0xa0e5000, v166
	s_waitcnt lgkmcnt(0)
	v_mfma_f32_32x32x16_bf16 v[32:47], v[22:25], v[120:123], v[32:47]
	ds_read_b128 v[18:21], v194 offset:32768
	ds_read_b128 v[22:25], v194 offset:40960
	s_waitcnt vmcnt(0) lgkmcnt(1)
	v_mfma_f32_32x32x16_bf16 v[0:15], v[18:21], v[124:127], v[0:15]
	ds_read_b128 v[18:21], v195
	s_waitcnt lgkmcnt(1)
	v_mfma_f32_32x32x16_bf16 v[32:47], v[22:25], v[124:127], v[32:47]
	v_or_b32_e32 v22, v183, v177
	ds_read_b128 v[22:25], v22
	ds_read_b128 v[26:29], v196
	ds_read_b128 v[52:55], v197
	s_waitcnt lgkmcnt(2)
	v_mfma_f32_32x32x16_bf16 v[0:15], v[18:21], v[22:25], v[0:15]
	v_or_b32_e32 v18, v183, v161
	ds_read_b128 v[18:21], v18
	s_waitcnt lgkmcnt(2)
	v_mfma_f32_32x32x16_bf16 v[32:47], v[26:29], v[22:25], v[32:47]
	v_add_co_u32_e32 v22, vcc, s2, v16
	s_mov_b32 s2, 0x60000
	s_nop 0
	v_addc_co_u32_e32 v23, vcc, 0, v17, vcc
	v_add_co_u32_e32 v16, vcc, s2, v16
	s_movk_i32 s2, 0x2000
	s_nop 0
	v_addc_co_u32_e32 v17, vcc, 0, v17, vcc
	global_load_dwordx4 v[56:59], v[22:23], off
	global_load_dwordx4 v[60:63], v[16:17], off
	v_add_co_u32_e32 v16, vcc, s2, v30
	s_waitcnt lgkmcnt(0)
	v_mfma_f32_32x32x16_bf16 v[0:15], v[52:55], v[18:21], v[0:15]
	v_addc_co_u32_e32 v17, vcc, 0, v31, vcc
	global_load_dwordx4 v[64:67], v[16:17], off
	global_load_dwordx4 v[68:71], v50, s[6:7] offset:128
	global_load_dwordx4 v[52:55], v50, s[14:15] offset:128
	ds_read_b128 v[22:25], v198
	ds_read_b128 v[26:29], v199
	v_or_b32_e32 v16, v183, v180
	s_waitcnt lgkmcnt(1)
	v_mfma_f32_32x32x16_bf16 v[32:47], v[22:25], v[18:21], v[32:47]
	ds_read_b128 v[16:19], v16
	ds_read_b128 v[20:23], v200
	ds_read_b128 v[72:75], v201
	v_and_b32_e32 v30, 0x3fffffc0, v51
	v_mov_b32_e32 v24, 0x1c000
	v_lshl_add_u32 v178, v30, 2, v24
	v_mov_b32_e32 v51, v205
	s_mov_b32 s14, s12
	s_waitcnt lgkmcnt(2)
	v_mfma_f32_32x32x16_bf16 v[0:15], v[26:29], v[16:19], v[0:15]
	s_mov_b32 s15, s12
	s_mov_b32 s2, 4
	v_cmp_eq_u32_e64 s[6:7], 0, v174
	v_lshl_or_b32 v181, v176, 2, v178
	s_waitcnt lgkmcnt(1)
	v_mfma_f32_32x32x16_bf16 v[32:47], v[20:23], v[16:19], v[32:47]
	v_or_b32_e32 v16, v183, v179
	ds_read_b128 v[76:79], v202
	ds_read_b128 v[80:83], v16
	s_waitcnt vmcnt(0)
	s_waitcnt vmcnt(4)
	ds_write_b128 v184, v[56:59] offset:49152
	s_waitcnt vmcnt(3)
	ds_write_b128 v184, v[60:63] offset:57344
	s_waitcnt lgkmcnt(2)
	v_mfma_f32_32x32x16_bf16 v[0:15], v[72:75], v[80:83], v[0:15]
	s_waitcnt vmcnt(2)
	ds_write_b128 v203, v[64:67]
	s_waitcnt vmcnt(1)
	ds_write_b128 v185, v[68:71] offset:16384
	s_waitcnt vmcnt(0)
; #define SLOAD_KR(k0) do { const char* kb_ = (const char*)KNh + (size_t)(k0) * (LDK * 2); const char* kb2_ = kb_ + 32 * LDK * 2; const char* rb_ = (const char*)KRb + (size_t)(k0) * 128; \
;     ks0 = *reinterpret_cast<const bf16x8*>(kb_ + vo_k); ks1 = *reinterpret_cast<const bf16x8*>(kb2_ + vo_k);               \
;     rs0 = *reinterpret_cast<const bf16x8*>(rb_ + vo_r); } while (0)
; #define SLOAD(k0) do { SLOAD_KR(k0); SLOAD_V(k0); } while (0)
; #define SWRITE(b) do { SWRITE_KR(b); SWRITE_V(b); } while (0)
; #define SWAIT() asm volatile("s_waitcnt vmcnt(0)" ::: "memory")
; DEVI void partialSM(f32x16& p0, f32x16& p1, float& m_reg, float& mn, float& alpha) {
;   constexpr float C = ASCALE * 1.4426950408889634f;
;   float pmax = p0[0];
; #pragma unroll
;   for (int r = 1; r < 16; ++r) pmax = fmaxf(pmax, p0[r]);
; #pragma unroll
;   for (int r = 0; r < 16; ++r) pmax = fmaxf(pmax, p1[r]);
;   { auto rr = __builtin_amdgcn_permlane32_swap(__float_as_uint(pmax), __float_as_uint(pmax), false, false);
;     pmax = fmaxf(__uint_as_float(rr[0]), __uint_as_float(rr[1])); }
;   if (__builtin_expect(__all(pmax - m_reg <= ATHR / ASCALE), 1)) { mn = m_reg; alpha = 1.f; }
;   else { mn = fmaxf(m_reg, pmax); alpha = __builtin_amdgcn_exp2f((m_reg - mn) * C); m_reg = mn; }
;   float mnC = -mn * C;
; #pragma unroll
;   for (int r = 0; r < 16; ++r) p0[r] = fmaf(p0[r], C, mnC);
; #pragma unroll
;   for (int r = 0; r < 16; ++r) p1[r] = fmaf(p1[r], C, mnC);
; #pragma unroll
;   for (int r = 0; r < 16; ++r) p0[r] = __builtin_amdgcn_exp2f(p0[r]);
; }
; DEVI void attn_item(const u16* __restrict__ Qb, const u16* __restrict__ KNh, const u16* __restrict__ VTh, int Lpad, const u16* __restrict__ KRb,
;                     const u16* __restrict__ SZb, u16* __restrict__ AOb, int NT, char* lds, const int wid_s_) {
;     ...
;   qkt(pA0, pA1, K_lds, R_lds, qr, Qrs, r32, hi); partialSM(pA0, pA1, m_reg, mnA, alA);
;   SLOAD(64);
;   SWAIT(); SWRITE(1); __syncthreads();
;   for (int j = 1; j + 1 < NT; j += 2) {
;     SLOAD_KR((j + 1) * 64);
	ds_write_b128 v185, v[52:55] offset:24576
	v_mov_b64_e32 v[30:31], s[26:27]
	v_mov_b64_e32 v[28:29], s[24:25]
	s_nop 3
	v_max_f32_e32 v72, v1, v1
	v_max_f32_e32 v73, v0, v0
	v_mfma_f32_32x32x16_bf16 v[32:47], v[76:79], v[80:83], v[32:47]
	v_max_f32_e32 v72, v73, v72
	v_max3_f32 v72, v72, v2, v3
	v_max3_f32 v72, v72, v4, v5
	v_max3_f32 v72, v72, v6, v7
	v_max3_f32 v72, v72, v8, v9
	v_max3_f32 v72, v72, v10, v11
	v_max3_f32 v72, v72, v12, v13
	v_max3_f32 v72, v72, v14, v15
	s_nop 3
	v_max3_f32 v72, v72, v32, v33
	v_max3_f32 v72, v72, v34, v35
	v_max3_f32 v72, v72, v36, v37
	v_max3_f32 v72, v72, v38, v39
	v_max3_f32 v72, v72, v40, v41
	v_max3_f32 v72, v72, v42, v43
	v_max3_f32 v72, v72, v44, v45
	v_max3_f32 v72, v72, v46, v47
	v_mov_b32_e32 v73, v72
	s_nop 1
	v_permlane32_swap_b32_e32 v72, v73
	v_max_f32_e32 v73, v73, v73
	v_max_f32_e32 v72, v72, v72
	v_max_f32_e32 v72, v72, v73
	v_add_f32_e32 v73, 0x7149f2ca, v72
	v_cmp_ge_f32_e32 vcc, s91, v73
	s_cmp_eq_u64 vcc, exec
	v_max_f32_e32 v53, 0xf149f2ca, v72
	s_cselect_b64 vcc, -1, 0
	v_cndmask_b32_e32 v222, v53, v208, vcc
	v_mul_f32_e32 v52, 0xbdd53b94, v222
	v_fmamk_f32 v0, v0, 0x3dd53b94, v52
	v_exp_f32_e32 v231, v0
	v_fmamk_f32 v0, v1, 0x3dd53b94, v52
	v_exp_f32_e32 v235, v0
	v_fmamk_f32 v0, v2, 0x3dd53b94, v52
	v_exp_f32_e32 v230, v0
	v_fmamk_f32 v0, v3, 0x3dd53b94, v52
	v_exp_f32_e32 v232, v0
	v_fmamk_f32 v0, v4, 0x3dd53b94, v52
	v_exp_f32_e32 v233, v0
	v_fmamk_f32 v0, v5, 0x3dd53b94, v52
	v_exp_f32_e32 v236, v0
	v_fmamk_f32 v0, v6, 0x3dd53b94, v52
	v_exp_f32_e32 v234, v0
	v_fmamk_f32 v0, v7, 0x3dd53b94, v52
	v_exp_f32_e32 v237, v0
	v_fmamk_f32 v0, v8, 0x3dd53b94, v52
	v_exp_f32_e32 v156, v0
	v_fmamk_f32 v0, v9, 0x3dd53b94, v52
	v_exp_f32_e32 v157, v0
	v_fmamk_f32 v0, v10, 0x3dd53b94, v52
	v_exp_f32_e32 v158, v0
	v_fmamk_f32 v0, v11, 0x3dd53b94, v52
	v_exp_f32_e32 v159, v0
	v_fmamk_f32 v0, v12, 0x3dd53b94, v52
	v_exp_f32_e32 v228, v0
	v_fmamk_f32 v0, v13, 0x3dd53b94, v52
	v_exp_f32_e32 v229, v0
	v_fmamk_f32 v0, v14, 0x3dd53b94, v52
	v_sub_f32_e32 v1, 0xf149f2ca, v53
	v_mul_f32_e32 v1, 0x3dd53b94, v1
	v_exp_f32_e32 v154, v0
	v_mov_b32_e32 v0, s46
	v_mov_b64_e32 v[26:27], s[22:23]
	v_mov_b64_e32 v[24:25], s[20:21]
	v_mov_b64_e32 v[22:23], s[18:19]
	v_mov_b64_e32 v[20:21], s[16:17]
	v_mov_b64_e32 v[18:19], s[14:15]
	v_mov_b64_e32 v[16:17], s[12:13]
	v_exp_f32_e32 v1, v1
	v_mad_u64_u32 v[162:163], s[14:15], s64, v0, v[50:51]
	v_add_u32_e32 v162, s75, v162
	v_pk_fma_f32 v[144:145], v[46:47], s[80:81], v[52:53] op_sel_hi:[1,0,0]
	v_pk_fma_f32 v[140:141], v[44:45], s[80:81], v[52:53] op_sel_hi:[1,0,0]
	v_pk_fma_f32 v[146:147], v[42:43], s[80:81], v[52:53] op_sel_hi:[1,0,0]
	v_pk_fma_f32 v[142:143], v[40:41], s[80:81], v[52:53] op_sel_hi:[1,0,0]
	v_pk_fma_f32 v[148:149], v[38:39], s[80:81], v[52:53] op_sel_hi:[1,0,0]
	v_pk_fma_f32 v[150:151], v[36:37], s[80:81], v[52:53] op_sel_hi:[1,0,0]
	v_pk_fma_f32 v[152:153], v[34:35], s[80:81], v[52:53] op_sel_hi:[1,0,0]
	v_pk_fma_f32 v[80:81], v[32:33], s[80:81], v[52:53] op_sel_hi:[1,0,0]
	v_fmac_f32_e32 v52, 0x3dd53b94, v15
	s_lshl_b64 s[14:15], s[46:47], 1
	v_exp_f32_e32 v155, v52
	s_or_b32 s13, s14, 0x80
	v_mov_b32_e32 v0, s13
	v_cndmask_b32_e64 v220, v1, 1.0, vcc
	v_mad_u64_u32 v[164:165], s[16:17], s28, v0, v[50:51]
	s_mul_i32 s13, s28, s15
	s_or_b32 s8, s8, s1
	v_mov_b64_e32 v[62:63], v[30:31]
	v_mov_b64_e32 v[46:47], v[30:31]
	v_mov_b64_e32 v[0:1], v[16:17]
	v_add_u32_e32 v165, s13, v165
	v_add_u32_e32 v164, s75, v164
	v_lshl_add_u64 v[168:169], s[8:9], 0, v[204:205]
	v_add_u32_e32 v168, 0x22681000, v168
	v_mov_b64_e32 v[60:61], v[28:29]
	v_mov_b64_e32 v[58:59], v[26:27]
	v_mov_b64_e32 v[56:57], v[24:25]
	v_mov_b64_e32 v[54:55], v[22:23]
	v_mov_b64_e32 v[52:53], v[20:21]
	v_mov_b64_e32 v[50:51], v[18:19]
	v_mov_b64_e32 v[48:49], v[16:17]
	v_mov_b64_e32 v[44:45], v[28:29]
	v_mov_b64_e32 v[42:43], v[26:27]
	v_mov_b64_e32 v[40:41], v[24:25]
	v_mov_b64_e32 v[38:39], v[22:23]
	v_mov_b64_e32 v[36:37], v[20:21]
	v_mov_b64_e32 v[34:35], v[18:19]
	v_mov_b64_e32 v[32:33], v[16:17]
	v_mov_b64_e32 v[2:3], v[18:19]
	v_mov_b64_e32 v[4:5], v[20:21]
	v_mov_b64_e32 v[6:7], v[22:23]
	v_mov_b64_e32 v[8:9], v[24:25]
	v_mov_b64_e32 v[10:11], v[26:27]
	v_mov_b64_e32 v[12:13], v[28:29]
	v_mov_b64_e32 v[14:15], v[30:31]
	s_waitcnt lgkmcnt(0)
	v_add_u32_e32 v196, v183, v177
	v_add_u32_e32 v198, v183, v161
	v_add_u32_e32 v200, v183, v180
	v_add_u32_e32 v202, v183, v179
	global_load_dwordx4 v[128:131], v168, s[36:37] offset:3072
	v_add_u32_e32 v163, 0x20000, v168
	global_load_dwordx4 v[132:135], v163, s[36:37] offset:3072
	global_load_dwordx4 v[136:139], v166, s[36:37] offset:3072
	s_barrier
; DEVI void finishSM(f32x16& p0, f32x16& p1, float alpha, float& l_reg, bf16x8& pa0, bf16x8& pa1, bf16x8& pa2, bf16x8& pa3) {
; #pragma unroll
;   for (int r = 0; r < 16; ++r) p1[r] = __builtin_amdgcn_exp2f(p1[r]);
;   float ps = 0;
; #pragma unroll
;   for (int r = 0; r < 16; ++r) ps += p0[r];
; #pragma unroll
;   for (int r = 0; r < 16; ++r) ps += p1[r];
;   { auto rr = __builtin_amdgcn_permlane32_swap(__float_as_uint(ps), __float_as_uint(ps), false, false);
;     ps = __uint_as_float(rr[0]) + __uint_as_float(rr[1]); }
;   l_reg = l_reg * alpha + ps;
;     ...
;   PK4(p0, 0, pa0); PK4(p0, 8, pa1); PK4(p1, 0, pa2); PK4(p1, 8, pa3);
;     ...
; }
; DEVI void mask_tile(f32x16& p0, f32x16& p1, bool nv16) {
; #pragma unroll
;   for (int r = 0; r < 16; ++r) { if (!(nv16 && r < 8)) p0[r] = -1e30f; p1[r] = -1e30f; }
; }
; DEVI void qkt(f32x16& p0, f32x16& p1, const char* Ks, const char* Rs, const bf16x8* qr, const char* Qrs, int r32, int hi) {
;   p0 = f32x16{}; p1 = f32x16{};
; #pragma unroll
;   for (int d0 = 0; d0 < 8; ++d0) { int cb = (d0 * 16 + hi * 8) * 2;
;     bf16x8 b0 = *reinterpret_cast<const bf16x8*>(Ks + KSWZ(r32, cb));
;     bf16x8 b1 = *reinterpret_cast<const bf16x8*>(Ks + KSWZ(32 + r32, cb));
;     p0 = __builtin_amdgcn_mfma_f32_32x32x16_bf16(b0, qr[d0], p0, 0, 0, 0);
;     p1 = __builtin_amdgcn_mfma_f32_32x32x16_bf16(b1, qr[d0], p1, 0, 0, 0); }
; #pragma unroll
;   for (int d0 = 0; d0 < 4; ++d0) { int cb = (d0 * 16 + hi * 8) * 2;
;     bf16x8 b0 = *reinterpret_cast<const bf16x8*>(Rs + RSWZ(r32, cb));
;     bf16x8 b1 = *reinterpret_cast<const bf16x8*>(Rs + RSWZ(32 + r32, cb));
;     bf16x8 qf = *reinterpret_cast<const bf16x8*>(Qrs + RSWZ(r32, cb));
;     p0 = __builtin_amdgcn_mfma_f32_32x32x16_bf16(b0, qf, p0, 0, 0, 0);
;     p1 = __builtin_amdgcn_mfma_f32_32x32x16_bf16(b1, qf, p1, 0, 0, 0); }
; }
.LBB0_981:
	ds_read_b128 v[64:67], v187 offset:49152
	v_exp_f32_e32 v242, v80
	s_waitcnt lgkmcnt(0)
	v_mfma_f32_32x32x16_bf16 v[64:79], v[64:67], v[96:99], 0
	ds_read_b128 v[82:85], v187 offset:57344
	v_exp_f32_e32 v245, v81
	s_waitcnt lgkmcnt(0)
	v_mfma_f32_32x32x16_bf16 v[80:95], v[82:85], v[96:99], 0
	ds_read_b128 v[238:241], v188 offset:49152
	v_exp_f32_e32 v248, v152
	s_waitcnt lgkmcnt(0)
	v_mfma_f32_32x32x16_bf16 v[64:79], v[238:241], v[100:103], v[64:79]
	ds_read_b128 v[238:241], v188 offset:57344
	v_exp_f32_e32 v251, v153
	s_waitcnt lgkmcnt(0)
	v_mfma_f32_32x32x16_bf16 v[80:95], v[238:241], v[100:103], v[80:95]
	ds_read_b128 v[238:241], v189 offset:49152
	v_add_f32_e32 v152, 0, v231
	v_add_f32_e32 v152, v235, v152
	v_add_f32_e32 v152, v230, v152
	v_exp_f32_e32 v252, v150
	s_waitcnt lgkmcnt(0)
	v_mfma_f32_32x32x16_bf16 v[64:79], v[238:241], v[104:107], v[64:79]
	ds_read_b128 v[238:241], v189 offset:57344
	v_add_f32_e32 v150, v232, v152
	v_add_f32_e32 v150, v233, v150
	v_add_f32_e32 v221, v236, v150
	v_exp_f32_e32 v253, v151
	s_waitcnt lgkmcnt(0)
	v_mfma_f32_32x32x16_bf16 v[80:95], v[238:241], v[104:107], v[80:95]
	ds_read_b128 v[150:153], v190 offset:49152
	v_add_f32_e32 v221, v234, v221
	v_add_f32_e32 v221, v237, v221
	v_add_f32_e32 v221, v156, v221
	v_exp_f32_e32 v209, v148
	s_waitcnt lgkmcnt(0)
	v_mfma_f32_32x32x16_bf16 v[64:79], v[150:153], v[108:111], v[64:79]
	ds_read_b128 v[150:153], v190 offset:57344
	v_add_f32_e32 v148, v157, v221
	v_add_f32_e32 v148, v158, v148
	v_add_f32_e32 v221, v159, v148
	v_exp_f32_e32 v210, v149
	s_waitcnt lgkmcnt(0)
	v_mfma_f32_32x32x16_bf16 v[80:95], v[150:153], v[108:111], v[80:95]
	ds_read_b128 v[148:151], v191 offset:49152
	v_add_f32_e32 v152, v228, v221
	v_add_f32_e32 v152, v229, v152
	v_add_f32_e32 v152, v154, v152
	v_exp_f32_e32 v211, v142
	s_waitcnt lgkmcnt(0)
	v_mfma_f32_32x32x16_bf16 v[64:79], v[148:151], v[112:115], v[64:79]
	ds_read_b128 v[148:151], v191 offset:57344
	v_add_f32_e32 v142, v155, v152
	v_add_f32_e32 v142, v242, v142
	v_add_f32_e32 v142, v245, v142
	v_exp_f32_e32 v212, v143
	s_waitcnt lgkmcnt(0)
	v_mfma_f32_32x32x16_bf16 v[80:95], v[148:151], v[112:115], v[80:95]
	ds_read_b128 v[148:151], v192 offset:49152
	v_add_f32_e32 v142, v248, v142
	v_add_f32_e32 v142, v251, v142
	v_add_f32_e32 v142, v252, v142
	v_exp_f32_e32 v214, v146
	s_waitcnt lgkmcnt(0)
	v_mfma_f32_32x32x16_bf16 v[64:79], v[148:151], v[116:119], v[64:79]
	ds_read_b128 v[148:151], v192 offset:57344
	v_add_f32_e32 v142, v253, v142
	v_add_f32_e32 v142, v209, v142
	v_add_f32_e32 v142, v210, v142
	v_exp_f32_e32 v215, v147
	s_waitcnt lgkmcnt(0)
	v_mfma_f32_32x32x16_bf16 v[80:95], v[148:151], v[116:119], v[80:95]
	ds_read_b128 v[146:149], v193 offset:49152
	v_add_f32_e32 v142, v211, v142
	v_add_f32_e32 v142, v212, v142
	v_add_f32_e32 v142, v214, v142
	v_exp_f32_e32 v216, v140
	s_waitcnt lgkmcnt(0)
	v_mfma_f32_32x32x16_bf16 v[64:79], v[146:149], v[120:123], v[64:79]
	ds_read_b128 v[146:149], v193 offset:57344
	v_add_f32_e32 v142, v215, v142
	v_cvt_pk_bf16_f32 v140, v231, v235
	v_add_f32_e32 v142, v216, v142
	v_exp_f32_e32 v217, v141
	s_waitcnt lgkmcnt(0)
	v_mfma_f32_32x32x16_bf16 v[80:95], v[146:149], v[120:123], v[80:95]
	ds_read_b128 v[146:149], v194 offset:49152
	v_add_f32_e32 v143, v217, v142
	v_cvt_pk_bf16_f32 v141, v230, v232
	v_cvt_pk_bf16_f32 v142, v233, v236
	v_exp_f32_e32 v218, v144
	s_waitcnt lgkmcnt(0)
	v_mfma_f32_32x32x16_bf16 v[64:79], v[146:149], v[124:127], v[64:79]
	ds_read_b128 v[146:149], v194 offset:57344
	v_add_f32_e32 v144, v218, v143
	v_cvt_pk_bf16_f32 v143, v234, v237
	v_permlane32_swap_b32_e32 v140, v142
	v_exp_f32_e32 v219, v145
	s_waitcnt lgkmcnt(0)
	v_mfma_f32_32x32x16_bf16 v[80:95], v[146:149], v[124:127], v[80:95]
	ds_read_b128 v[148:151], v195 offset:8192
	v_add_f32_e32 v204, v219, v144
	v_permlane32_swap_b32_e32 v141, v143
	v_mov_b32_e32 v221, v204
	ds_read_b128 v[230:233], v195 offset:12288
	v_cvt_pk_bf16_f32 v144, v156, v157
	v_cvt_pk_bf16_f32 v145, v158, v159
	ds_read_b128 v[156:159], v196
	v_cvt_pk_bf16_f32 v146, v228, v229
	ds_read_b128 v[234:237], v198
	s_waitcnt lgkmcnt(1)
	v_mfma_f32_32x32x16_bf16 v[80:95], v[230:233], v[156:159], v[80:95]
	ds_read_b128 v[228:231], v197 offset:12288
	s_waitcnt lgkmcnt(0)
	v_mfma_f32_32x32x16_bf16 v[80:95], v[228:231], v[234:237], v[80:95]
	ds_read_b128 v[228:231], v199 offset:12288
	ds_read_b128 v[238:241], v200
	s_waitcnt lgkmcnt(0)
	v_mfma_f32_32x32x16_bf16 v[80:95], v[228:231], v[238:241], v[80:95]
	v_permlane32_swap_b32_e32 v204, v221
	v_cvt_pk_bf16_f32 v147, v154, v155
	v_permlane32_swap_b32_e32 v144, v146
	ds_read_b128 v[228:231], v201 offset:12288
	v_mfma_f32_32x32x16_bf16 v[64:79], v[148:151], v[156:159], v[64:79]
	v_permlane32_swap_b32_e32 v145, v147
	ds_read_b128 v[148:151], v197 offset:8192
	v_cvt_pk_bf16_f32 v155, v218, v219
	ds_read_b128 v[156:159], v202
	s_waitcnt lgkmcnt(1)
	v_mfma_f32_32x32x16_bf16 v[64:79], v[148:151], v[234:237], v[64:79]
	ds_read_b128 v[148:151], v199 offset:8192
	v_cvt_pk_bf16_f32 v154, v216, v217
	s_waitcnt lgkmcnt(0)
	v_mfma_f32_32x32x16_bf16 v[64:79], v[148:151], v[238:241], v[64:79]
	ds_read_b128 v[150:153], v201 offset:8192
	s_waitcnt lgkmcnt(0)
; #define SBAR() __builtin_amdgcn_sched_barrier(0)
; #define SLOAD_V(k0) do { const char* vb_ = (const char*)VTh + (size_t)(k0) * 2; const char* vb2_ = vb_ + vhalf;                \
;     vs0 = *reinterpret_cast<const bf16x8*>(vb_ + vo_v); vs1 = *reinterpret_cast<const bf16x8*>(vb2_ + vo_v); } while (0)
; #define SWRITE_KR(b) do { int kc = sc * 2; *(bf16x8*)(K_lds + (b) * SHM_K + KSWZ(sr, kc)) = ks0; *(bf16x8*)(K_lds + (b) * SHM_K + KSWZ(32 + sr, kc)) = ks1; \
;     *(bf16x8*)(R_lds + (b) * SHM_R + RSWZ(rr_, rc_ * 2)) = rs0; } while (0)
; #define SWRITE_V(b) do { *(bf16x8*)(V_lds + (b) * SHM_V + RSWZ(vd, vc * 16)) = vs0; *(bf16x8*)(V_lds + (b) * SHM_V + RSWZ(vd + 64, vc * 16)) = vs1; } while (0)
; #define SWAIT() asm volatile("s_waitcnt vmcnt(0)" ::: "memory")
; DEVI void pv_d0(f32x16* o, const char* Vs, int r32, int hi, bf16x8 pa0, bf16x8 pa1, bf16x8 pa2, bf16x8 pa3) {
; #pragma unroll
;   for (int d0 = 0; d0 < 4; ++d0) {
;     const bf16x8 f0 = *reinterpret_cast<const bf16x8*>(Vs + RSWZ(d0 * 32 + r32, (0 * 16 + hi * 8) * 2));
;     const bf16x8 f1 = *reinterpret_cast<const bf16x8*>(Vs + RSWZ(d0 * 32 + r32, (1 * 16 + hi * 8) * 2));
;     const bf16x8 f2 = *reinterpret_cast<const bf16x8*>(Vs + RSWZ(d0 * 32 + r32, (2 * 16 + hi * 8) * 2));
;     const bf16x8 f3 = *reinterpret_cast<const bf16x8*>(Vs + RSWZ(d0 * 32 + r32, (3 * 16 + hi * 8) * 2));
;     o[d0] = __builtin_amdgcn_mfma_f32_32x32x16_bf16(pa0, f0, o[d0], 0, 0, 0);
;     o[d0] = __builtin_amdgcn_mfma_f32_32x32x16_bf16(pa1, f1, o[d0], 0, 0, 0);
;     o[d0] = __builtin_amdgcn_mfma_f32_32x32x16_bf16(pa2, f2, o[d0], 0, 0, 0);
;     o[d0] = __builtin_amdgcn_mfma_f32_32x32x16_bf16(pa3, f3, o[d0], 0, 0, 0);
;   }
; }
; DEVI void attn_item(const u16* __restrict__ Qb, const u16* __restrict__ KNh, const u16* __restrict__ VTh, int Lpad, const u16* __restrict__ KRb,
;                     const u16* __restrict__ SZb, u16* __restrict__ AOb, int NT, char* lds, const int wid_s_) {
;     ...
;     SLOAD_V((j + 1) * 64); SBAR();
;     pv_d0(o, V_lds, r32, hi, pa0, pa1, pa2, pa3); partialSM(pB0, pB1, m_reg, mnB, alB);
;     SWRITE_KR(0);
;     __syncthreads(); SWAIT(); SWRITE_V(0);
;     RESC(alB); __syncthreads();
	v_mfma_f32_32x32x16_bf16 v[64:79], v[150:153], v[156:159], v[64:79]
	v_cvt_pk_bf16_f32 v153, v214, v215
	v_cvt_pk_bf16_f32 v152, v211, v212
	v_cvt_pk_bf16_f32 v151, v209, v210
	v_cvt_pk_bf16_f32 v149, v248, v251
	s_nop 1
	v_permlane32_swap_b32_e32 v149, v151
	v_cvt_pk_bf16_f32 v148, v242, v245
	v_mfma_f32_32x32x16_bf16 v[80:95], v[228:231], v[156:159], v[80:95]
	v_cvt_pk_bf16_f32 v150, v252, v253
	s_nop 1
	v_permlane32_swap_b32_e32 v148, v150
	v_permlane32_swap_b32_e32 v152, v154
	v_permlane32_swap_b32_e32 v153, v155
	global_load_dwordx4 v[228:231], v162, s[36:37] offset:3328
	global_load_dwordx4 v[232:235], v164, s[36:37] offset:3328
	ds_read_b128 v[236:239], v177
	ds_read_b128 v[240:243], v161
	ds_read_b128 v[244:247], v180
	ds_read_b128 v[248:251], v179
	s_waitcnt lgkmcnt(3)
	v_mfma_f32_32x32x16_bf16 v[16:31], v[140:143], v[236:239], v[16:31]
	ds_read_b128 v[236:239], v177 offset:4096
	s_waitcnt lgkmcnt(3)
	v_mfma_f32_32x32x16_bf16 v[16:31], v[144:147], v[240:243], v[16:31]
	ds_read_b128 v[240:243], v161 offset:4096
	s_waitcnt lgkmcnt(1)
	v_mfma_f32_32x32x16_bf16 v[48:63], v[140:143], v[236:239], v[48:63]
	ds_read_b128 v[236:239], v177 offset:8192
	v_mfma_f32_32x32x16_bf16 v[16:31], v[148:151], v[244:247], v[16:31]
	ds_read_b128 v[244:247], v180 offset:4096
	s_waitcnt lgkmcnt(2)
	v_mfma_f32_32x32x16_bf16 v[48:63], v[144:147], v[240:243], v[48:63]
	ds_read_b128 v[240:243], v161 offset:8192
	s_waitcnt lgkmcnt(2)
	v_mfma_f32_32x32x16_bf16 v[32:47], v[140:143], v[236:239], v[32:47]
	ds_read_b128 v[236:239], v177 offset:12288
	v_mfma_f32_32x32x16_bf16 v[16:31], v[152:155], v[248:251], v[16:31]
	ds_read_b128 v[248:251], v179 offset:4096
	s_waitcnt lgkmcnt(3)
	v_mfma_f32_32x32x16_bf16 v[48:63], v[148:151], v[244:247], v[48:63]
	ds_read_b128 v[244:247], v180 offset:8192
	s_waitcnt lgkmcnt(3)
	v_mfma_f32_32x32x16_bf16 v[32:47], v[144:147], v[240:243], v[32:47]
	ds_read_b128 v[240:243], v161 offset:12288
	s_waitcnt lgkmcnt(3)
	v_mfma_f32_32x32x16_bf16 v[0:15], v[140:143], v[236:239], v[0:15]
	v_max_f32_e32 v140, v65, v65
	v_max_f32_e32 v141, v64, v64
	v_max_f32_e32 v140, v141, v140
	v_max3_f32 v140, v140, v66, v67
	v_max3_f32 v140, v140, v68, v69
	v_max3_f32 v140, v140, v70, v71
	v_max3_f32 v140, v140, v72, v73
	v_max3_f32 v140, v140, v74, v75
	v_max3_f32 v140, v140, v76, v77
	s_waitcnt lgkmcnt(2)
	v_mfma_f32_32x32x16_bf16 v[48:63], v[152:155], v[248:251], v[48:63]
	ds_read_b128 v[248:251], v179 offset:8192
	v_max3_f32 v140, v140, v78, v79
	v_max3_f32 v140, v140, v80, v81
	v_max3_f32 v140, v140, v82, v83
	v_max3_f32 v140, v140, v84, v85
	v_max3_f32 v140, v140, v86, v87
	v_max3_f32 v140, v140, v88, v89
	s_waitcnt lgkmcnt(2)
	v_mfma_f32_32x32x16_bf16 v[32:47], v[148:151], v[244:247], v[32:47]
	ds_read_b128 v[244:247], v180 offset:12288
	v_max3_f32 v140, v140, v90, v91
	v_max3_f32 v140, v140, v92, v93
	v_max3_f32 v140, v140, v94, v95
	v_mov_b32_e32 v141, v140
	s_nop 1
	v_permlane32_swap_b32_e32 v140, v141
	s_waitcnt lgkmcnt(2)
	v_mfma_f32_32x32x16_bf16 v[0:15], v[144:147], v[240:243], v[0:15]
	v_max_f32_e32 v141, v141, v141
	v_max_f32_e32 v140, v140, v140
	v_max_f32_e32 v140, v140, v141
	v_sub_f32_e32 v141, v140, v222
	v_cmp_ge_f32_e32 vcc, s91, v141
	v_max_f32_e32 v141, v222, v222
	v_max_f32_e32 v140, v141, v140
	s_waitcnt lgkmcnt(1)
	v_mfma_f32_32x32x16_bf16 v[32:47], v[152:155], v[248:251], v[32:47]
	ds_read_b128 v[248:251], v179 offset:12288
	v_sub_f32_e32 v141, v222, v140
	v_mul_f32_e32 v141, 0x3dd53b94, v141
	v_exp_f32_e32 v141, v141
	s_cmp_eq_u64 vcc, exec
	s_cselect_b64 s[8:9], -1, 0
	s_waitcnt lgkmcnt(1)
	v_mfma_f32_32x32x16_bf16 v[0:15], v[148:151], v[244:247], v[0:15]
	s_waitcnt lgkmcnt(0)
	s_barrier
	s_waitcnt vmcnt(0)
	v_cndmask_b32_e64 v224, v141, 1.0, s[8:9]
	v_mfma_f32_32x32x16_bf16 v[0:15], v[152:155], v[248:251], v[0:15]
	v_cmp_gt_f32_e32 vcc, 1.0, v224
	ds_write_b128 v184, v[128:131] offset:32768
	ds_write_b128 v184, v[132:135] offset:40960
	ds_write_b128 v186, v[136:139]
	ds_write_b128 v185, v[228:231]
	ds_write_b128 v185, v[232:235] offset:8192
	s_cbranch_vccz .LBB0_985
	s_and_saveexec_b64 s[14:15], s[6:7]
	ds_write_b32 v181, v224 offset:128
	s_or_b64 exec, exec, s[14:15]
	s_waitcnt lgkmcnt(0)
	v_add_u32_e32 v141, v178, v160
	ds_read_b128 v[128:131], v141 offset:224
	ds_read_b128 v[132:135], v141 offset:192
	ds_read_b128 v[136:139], v141 offset:160
	ds_read_b128 v[142:145], v141 offset:128
	s_waitcnt lgkmcnt(3)
	v_pk_mul_f32 v[28:29], v[28:29], v[128:129]
	s_waitcnt lgkmcnt(2)
	v_pk_mul_f32 v[24:25], v[24:25], v[132:133]
	s_waitcnt lgkmcnt(1)
	v_pk_mul_f32 v[20:21], v[20:21], v[136:137]
	v_pk_mul_f32 v[30:31], v[30:31], v[130:131]
	v_pk_mul_f32 v[26:27], v[26:27], v[134:135]
	v_pk_mul_f32 v[22:23], v[22:23], v[138:139]
	s_waitcnt lgkmcnt(0)
	v_pk_mul_f32 v[18:19], v[18:19], v[144:145]
	v_pk_mul_f32 v[16:17], v[16:17], v[142:143]
	v_pk_mul_f32 v[60:61], v[60:61], v[128:129]
	v_pk_mul_f32 v[56:57], v[56:57], v[132:133]
	v_pk_mul_f32 v[52:53], v[52:53], v[136:137]
	v_pk_mul_f32 v[62:63], v[62:63], v[130:131]
	v_pk_mul_f32 v[58:59], v[58:59], v[134:135]
	v_pk_mul_f32 v[54:55], v[54:55], v[138:139]
	v_pk_mul_f32 v[50:51], v[50:51], v[144:145]
	v_pk_mul_f32 v[48:49], v[48:49], v[142:143]
	v_pk_mul_f32 v[44:45], v[44:45], v[128:129]
	v_pk_mul_f32 v[40:41], v[40:41], v[132:133]
	v_pk_mul_f32 v[36:37], v[36:37], v[136:137]
	v_pk_mul_f32 v[46:47], v[46:47], v[130:131]
	v_pk_mul_f32 v[42:43], v[42:43], v[134:135]
	v_pk_mul_f32 v[38:39], v[38:39], v[138:139]
	v_pk_mul_f32 v[34:35], v[34:35], v[144:145]
	v_pk_mul_f32 v[32:33], v[32:33], v[142:143]
	v_pk_mul_f32 v[12:13], v[12:13], v[128:129]
	v_pk_mul_f32 v[8:9], v[8:9], v[132:133]
	v_pk_mul_f32 v[4:5], v[4:5], v[136:137]
	v_pk_mul_f32 v[14:15], v[14:15], v[130:131]
	v_pk_mul_f32 v[10:11], v[10:11], v[134:135]
	v_pk_mul_f32 v[6:7], v[6:7], v[138:139]
	v_pk_mul_f32 v[2:3], v[2:3], v[144:145]
	v_pk_mul_f32 v[0:1], v[0:1], v[142:143]

; #define SWRITE_KR(b) do { int kc = sc * 2; *(bf16x8*)(K_lds + (b) * SHM_K + KSWZ(sr, kc)) = ks0; *(bf16x8*)(K_lds + (b) * SHM_K + KSWZ(32 + sr, kc)) = ks1; \
;     *(bf16x8*)(R_lds + (b) * SHM_R + RSWZ(rr_, rc_ * 2)) = rs0; } while (0)
; #define SWRITE_V(b) do { *(bf16x8*)(V_lds + (b) * SHM_V + RSWZ(vd, vc * 16)) = vs0; *(bf16x8*)(V_lds + (b) * SHM_V + RSWZ(vd + 64, vc * 16)) = vs1; } while (0)
; #define SWAIT() asm volatile("s_waitcnt vmcnt(0)" ::: "memory")
; #define RESC(a) do { if (__any((a) < 1.f)) { if (hi == 0) al_l[r32] = (a); asm volatile("s_waitcnt lgkmcnt(0)" ::: "memory"); \
;     _Pragma("unroll") for (int d = 0; d < 4; ++d) _Pragma("unroll") for (int r = 0; r < 16; ++r) o[d][r] *= al_l[crow(r, hi)]; } } while (0)
; DEVI void partialSM(f32x16& p0, f32x16& p1, float& m_reg, float& mn, float& alpha) {
;     ...
;   float mnC = -mn * C;
; #pragma unroll
;   for (int r = 0; r < 16; ++r) p0[r] = fmaf(p0[r], C, mnC);
; #pragma unroll
;   for (int r = 0; r < 16; ++r) p1[r] = fmaf(p1[r], C, mnC);
; #pragma unroll
;   for (int r = 0; r < 16; ++r) p0[r] = __builtin_amdgcn_exp2f(p0[r]);
; DEVI void attn_item(const u16* __restrict__ Qb, const u16* __restrict__ KNh, const u16* __restrict__ VTh, int Lpad, const u16* __restrict__ KRb,
;                     const u16* __restrict__ SZb, u16* __restrict__ AOb, int NT, char* lds, const int wid_s_) {
;     ...
;     SWRITE_KR(1);
;     __syncthreads(); SWAIT(); SWRITE_V(1);
;     RESC(alA); __syncthreads();
;   }
.LBB0_989:
	v_cndmask_b32_e64 v222, v89, v222, s[8:9]
	v_mul_f32_e32 v90, 0xbdd53b94, v222
	v_mov_b32_e32 v129, v90
	v_fmamk_f32 v64, v64, 0x3dd53b94, v90
	v_fmamk_f32 v65, v65, 0x3dd53b94, v90
	v_fmamk_f32 v66, v66, 0x3dd53b94, v90
	v_fmamk_f32 v67, v67, 0x3dd53b94, v90
	v_fmamk_f32 v68, v68, 0x3dd53b94, v90
	v_fmamk_f32 v69, v69, 0x3dd53b94, v90
	v_fmamk_f32 v70, v70, 0x3dd53b94, v90
	v_fmamk_f32 v71, v71, 0x3dd53b94, v90
	v_fmamk_f32 v89, v229, 0x3dd53b94, v90
	v_fmamk_f32 v91, v228, 0x3dd53b94, v90
	v_fmamk_f32 v92, v226, 0x3dd53b94, v90
	v_fmamk_f32 v93, v225, 0x3dd53b94, v90
	v_fmamk_f32 v94, v227, 0x3dd53b94, v90
	v_fmamk_f32 v95, v223, 0x3dd53b94, v90
	v_fmamk_f32 v128, v173, 0x3dd53b94, v90
	v_fmac_f32_e32 v129, 0x3dd53b94, v172
	v_exp_f32_e32 v231, v64
	v_exp_f32_e32 v235, v65
	v_exp_f32_e32 v230, v66
	v_exp_f32_e32 v232, v67
	v_exp_f32_e32 v233, v68
	v_exp_f32_e32 v236, v69
	v_exp_f32_e32 v234, v70
	v_exp_f32_e32 v237, v71
	v_exp_f32_e32 v156, v89
	v_exp_f32_e32 v157, v91
	v_exp_f32_e32 v158, v92
	v_exp_f32_e32 v159, v93
	v_exp_f32_e32 v228, v94
	v_exp_f32_e32 v229, v95
	v_exp_f32_e32 v154, v128
	v_exp_f32_e32 v155, v129
	v_add_f32_e32 v64, v204, v221
	v_fmac_f32_e32 v64, v220, v182
	v_add_f32_e32 v182, v170, v171
	v_add_u32_e32 v166, 0x4000, v166
	s_add_i32 s1, s2, 2
	v_pk_fma_f32 v[80:81], v[80:81], s[80:81], v[90:91] op_sel_hi:[1,0,0]
	v_pk_fma_f32 v[152:153], v[82:83], s[80:81], v[90:91] op_sel_hi:[1,0,0]
	v_pk_fma_f32 v[150:151], v[84:85], s[80:81], v[90:91] op_sel_hi:[1,0,0]
	v_pk_fma_f32 v[148:149], v[86:87], s[80:81], v[90:91] op_sel_hi:[1,0,0]
	v_pk_fma_f32 v[142:143], v[78:79], s[80:81], v[90:91] op_sel_hi:[1,0,0]
	v_pk_fma_f32 v[146:147], v[76:77], s[80:81], v[90:91] op_sel_hi:[1,0,0]
	v_pk_fma_f32 v[140:141], v[74:75], s[80:81], v[90:91] op_sel_hi:[1,0,0]
	v_pk_fma_f32 v[144:145], v[72:73], s[80:81], v[90:91] op_sel_hi:[1,0,0]
	v_fmac_f32_e32 v182, v64, v224
	v_add_u32_e32 v162, s82, v162
	v_add_u32_e32 v164, s82, v164
	s_cmp_ge_u32 s2, s4
	v_add_u32_e32 v168, 0x80000, v168
	s_cbranch_scc1 .Lhl_skip
	global_load_dwordx4 v[128:131], v168, s[36:37] offset:3072
	v_add_u32_e32 v163, 0x20000, v168
	global_load_dwordx4 v[132:135], v163, s[36:37] offset:3072
	global_load_dwordx4 v[136:139], v166, s[36:37] offset:3072
.Lhl_skip:
	s_waitcnt lgkmcnt(0)
	s_barrier
	s_cbranch_scc1 .LBB0_991
	s_mov_b32 s2, s1
	v_mov_b32_e32 v220, v88
	s_branch .LBB0_981
